# EpiPair0 epilogue: 8 SSQ row-scale loads hoisted to epilogue start (one wait instead of 8 serialized vmcnt(0))
# speedup vs baseline: 1.0060x; 1.0060x over previous
.LBB0_314:
	v_lshl_add_u32 v140, s2, 8, v142
	v_ashrrev_i32_e32 v141, 31, v140
	v_lshl_add_u64 v[156:157], v[140:141], 4, s[48:49]
	global_load_dwordx4 v[212:215], v[156:157], off offset:256
	global_load_dwordx4 v[216:219], v[156:157], off offset:512
	global_load_dwordx4 v[220:223], v[156:157], off offset:768
	global_load_dwordx4 v[224:227], v[156:157], off offset:2048
	global_load_dwordx4 v[228:231], v[156:157], off offset:2304
	global_load_dwordx4 v[232:235], v[156:157], off offset:2560
	global_load_dwordx4 v[236:239], v[156:157], off offset:2816
	global_load_dwordx4 v[156:159], v[156:157], off
	v_lshl_or_b32 v164, s3, 8, v154
	v_mov_b64_e32 v[138:139], s[46:47]
	v_mad_i64_i32 v[160:161], s[2:3], v140, s78, v[138:139]
	s_andn2_b64 vcc, exec, s[38:39]
	s_waitcnt vmcnt(0)
	v_mov_b32_e32 v162, v157
	v_mov_b32_e32 v163, v158
	v_mov_b32_e32 v157, v159
	v_pk_add_f32 v[156:157], v[162:163], v[156:157]
	s_nop 0
	v_add_f32_e32 v141, v156, v157
	v_fmamk_f32 v141, v141, 0x3a800000, v184
	v_rsq_f32_e32 v156, v141
	s_nop 0
	v_pk_mul_f32 v[124:125], v[124:125], v[156:157] op_sel_hi:[1,0]
	s_nop 0
	v_mul_f32_e32 v141, 0xbfb8aa3b, v124
	v_exp_f32_e32 v141, v141
	v_pk_mul_f32 v[120:121], v[120:121], v[156:157] op_sel_hi:[1,0]
	v_pk_mul_f32 v[122:123], v[122:123], v[156:157] op_sel_hi:[1,0]
	v_pk_mul_f32 v[116:117], v[116:117], v[156:157] op_sel_hi:[1,0]
	v_add_f32_e32 v141, 1.0, v141
	v_rcp_f32_e32 v158, v141
	v_mul_f32_e32 v141, 0xbfb8aa3b, v125
	v_exp_f32_e32 v141, v141
	v_pk_mul_f32 v[112:113], v[112:113], v[156:157] op_sel_hi:[1,0]
	v_pk_mul_f32 v[114:115], v[114:115], v[156:157] op_sel_hi:[1,0]
	v_add_f32_e32 v141, 1.0, v141
	v_rcp_f32_e32 v159, v141
	s_nop 0
	v_pk_mul_f32 v[124:125], v[124:125], v[158:159]
	s_nop 0
	v_pk_mul_f32 v[120:121], v[120:121], v[124:125]
	v_pk_mul_f32 v[124:125], v[126:127], v[156:157] op_sel_hi:[1,0]
	s_nop 0
	v_mul_f32_e32 v126, 0xbfb8aa3b, v124
	v_mul_f32_e32 v127, 0xbfb8aa3b, v125
	v_exp_f32_e32 v126, v126
	v_exp_f32_e32 v127, v127
	v_add_f32_e32 v126, 1.0, v126
	v_add_f32_e32 v127, 1.0, v127
	v_rcp_f32_e32 v126, v126
	v_rcp_f32_e32 v127, v127
	s_nop 0
	v_pk_mul_f32 v[124:125], v[124:125], v[126:127]
	s_nop 0
	v_pk_mul_f32 v[122:123], v[122:123], v[124:125]
	v_cvt_pk_bf16_f32 v124, v120, v121
	v_ashrrev_i32_e32 v120, 1, v164
	v_ashrrev_i32_e32 v121, 31, v120
	v_lshlrev_b64 v[120:121], 1, v[120:121]
	v_cvt_pk_bf16_f32 v125, v122, v123
	v_lshl_add_u64 v[122:123], v[160:161], 0, v[120:121]
	global_store_dwordx2 v[122:123], v[124:125], off
	v_mul_f32_e32 v124, 0xbfb8aa3b, v116
	v_mul_f32_e32 v125, 0xbfb8aa3b, v117
	v_exp_f32_e32 v124, v124
	v_exp_f32_e32 v125, v125
	v_add_f32_e32 v124, 1.0, v124
	v_add_f32_e32 v125, 1.0, v125
	v_rcp_f32_e32 v124, v124
	v_rcp_f32_e32 v125, v125
	s_nop 0
	v_pk_mul_f32 v[116:117], v[116:117], v[124:125]
	s_nop 0
	v_pk_mul_f32 v[112:113], v[112:113], v[116:117]
	v_pk_mul_f32 v[116:117], v[118:119], v[156:157] op_sel_hi:[1,0]
	v_cvt_pk_bf16_f32 v112, v112, v113
	v_mul_f32_e32 v118, 0xbfb8aa3b, v116
	v_mul_f32_e32 v119, 0xbfb8aa3b, v117
	v_exp_f32_e32 v118, v118
	v_exp_f32_e32 v119, v119
	v_add_f32_e32 v118, 1.0, v118
	v_add_f32_e32 v119, 1.0, v119
	v_rcp_f32_e32 v118, v118
	v_rcp_f32_e32 v119, v119
	s_nop 0
	v_pk_mul_f32 v[116:117], v[116:117], v[118:119]
	s_nop 0
	v_pk_mul_f32 v[114:115], v[114:115], v[116:117]
	s_nop 0
	v_cvt_pk_bf16_f32 v113, v114, v115
	v_or_b32_e32 v114, 16, v140
	v_ashrrev_i32_e32 v115, 31, v114
	global_store_dwordx2 v[122:123], v[112:113], off offset:128
	v_mad_i64_i32 v[112:113], s[2:3], v114, s78, v[138:139]
	v_mov_b32_e32 v114, v212
	v_mov_b32_e32 v115, v213
	v_mov_b32_e32 v116, v214
	v_mov_b32_e32 v117, v215
	v_mov_b32_e32 v118, v115
	v_mov_b32_e32 v119, v116
	v_mov_b32_e32 v115, v117
	v_pk_add_f32 v[114:115], v[118:119], v[114:115]
	s_nop 0
	v_add_f32_e32 v114, v114, v115
	v_fmamk_f32 v114, v114, 0x3a800000, v184
	v_rsq_f32_e32 v114, v114
	s_nop 0
	v_pk_mul_f32 v[108:109], v[108:109], v[114:115] op_sel_hi:[1,0]
	s_nop 0
	v_mul_f32_e32 v115, 0xbfb8aa3b, v108
	v_exp_f32_e32 v115, v115
	s_nop 0
	v_add_f32_e32 v115, 1.0, v115
	v_rcp_f32_e32 v116, v115
	v_mul_f32_e32 v115, 0xbfb8aa3b, v109
	v_exp_f32_e32 v115, v115
	s_nop 0
	v_add_f32_e32 v115, 1.0, v115
	v_rcp_f32_e32 v117, v115
	v_pk_mul_f32 v[104:105], v[104:105], v[114:115] op_sel_hi:[1,0]
	v_pk_mul_f32 v[106:107], v[106:107], v[114:115] op_sel_hi:[1,0]
	v_pk_mul_f32 v[100:101], v[100:101], v[114:115] op_sel_hi:[1,0]
	v_pk_mul_f32 v[108:109], v[108:109], v[116:117]
	v_pk_mul_f32 v[96:97], v[96:97], v[114:115] op_sel_hi:[1,0]
	v_pk_mul_f32 v[104:105], v[104:105], v[108:109]
	v_pk_mul_f32 v[108:109], v[110:111], v[114:115] op_sel_hi:[1,0]
	v_cvt_pk_bf16_f32 v104, v104, v105
	v_mul_f32_e32 v110, 0xbfb8aa3b, v108
	v_mul_f32_e32 v111, 0xbfb8aa3b, v109
	v_exp_f32_e32 v110, v110
	v_exp_f32_e32 v111, v111
	v_pk_mul_f32 v[98:99], v[98:99], v[114:115] op_sel_hi:[1,0]
	v_add_f32_e32 v110, 1.0, v110
	v_add_f32_e32 v111, 1.0, v111
	v_rcp_f32_e32 v110, v110
	v_rcp_f32_e32 v111, v111
	s_nop 0
	v_pk_mul_f32 v[108:109], v[108:109], v[110:111]
	s_nop 0
	v_pk_mul_f32 v[106:107], v[106:107], v[108:109]
	s_nop 0
	v_cvt_pk_bf16_f32 v105, v106, v107
	v_lshl_add_u64 v[106:107], v[112:113], 0, v[120:121]
	global_store_dwordx2 v[106:107], v[104:105], off
	v_mul_f32_e32 v104, 0xbfb8aa3b, v100
	v_mul_f32_e32 v105, 0xbfb8aa3b, v101
	v_exp_f32_e32 v104, v104
	v_exp_f32_e32 v105, v105
	v_add_f32_e32 v104, 1.0, v104
	v_add_f32_e32 v105, 1.0, v105
	v_rcp_f32_e32 v104, v104
	v_rcp_f32_e32 v105, v105
	s_nop 0
	v_pk_mul_f32 v[100:101], v[100:101], v[104:105]
	s_nop 0
	v_pk_mul_f32 v[96:97], v[96:97], v[100:101]
	v_pk_mul_f32 v[100:101], v[102:103], v[114:115] op_sel_hi:[1,0]
	v_cvt_pk_bf16_f32 v96, v96, v97
	v_mul_f32_e32 v102, 0xbfb8aa3b, v100
	v_mul_f32_e32 v103, 0xbfb8aa3b, v101
	v_exp_f32_e32 v102, v102
	v_exp_f32_e32 v103, v103
	v_add_f32_e32 v102, 1.0, v102
	v_add_f32_e32 v103, 1.0, v103
	v_rcp_f32_e32 v102, v102
	v_rcp_f32_e32 v103, v103
	s_nop 0
	v_pk_mul_f32 v[100:101], v[100:101], v[102:103]
	s_nop 0
	v_pk_mul_f32 v[98:99], v[98:99], v[100:101]
	s_nop 0
	v_cvt_pk_bf16_f32 v97, v98, v99
	v_or_b32_e32 v98, 32, v140
	v_ashrrev_i32_e32 v99, 31, v98
	global_store_dwordx2 v[106:107], v[96:97], off offset:128
	v_mad_i64_i32 v[96:97], s[2:3], v98, s78, v[138:139]
	v_mov_b32_e32 v98, v216
	v_mov_b32_e32 v99, v217
	v_mov_b32_e32 v100, v218
	v_mov_b32_e32 v101, v219
	v_mov_b32_e32 v102, v99
	v_mov_b32_e32 v103, v100
	v_mov_b32_e32 v99, v101
	v_pk_add_f32 v[98:99], v[102:103], v[98:99]
	s_nop 0
	v_add_f32_e32 v98, v98, v99
	v_fmamk_f32 v98, v98, 0x3a800000, v184
	v_rsq_f32_e32 v98, v98
	s_nop 0
	v_pk_mul_f32 v[92:93], v[92:93], v[98:99] op_sel_hi:[1,0]
	s_nop 0
	v_mul_f32_e32 v99, 0xbfb8aa3b, v92
	v_exp_f32_e32 v99, v99
	s_nop 0
	v_add_f32_e32 v99, 1.0, v99
	v_rcp_f32_e32 v100, v99
	v_mul_f32_e32 v99, 0xbfb8aa3b, v93
	v_exp_f32_e32 v99, v99
	s_nop 0
	v_add_f32_e32 v99, 1.0, v99
	v_rcp_f32_e32 v101, v99
	v_pk_mul_f32 v[88:89], v[88:89], v[98:99] op_sel_hi:[1,0]
	v_pk_mul_f32 v[90:91], v[90:91], v[98:99] op_sel_hi:[1,0]
	v_pk_mul_f32 v[84:85], v[84:85], v[98:99] op_sel_hi:[1,0]
	v_pk_mul_f32 v[92:93], v[92:93], v[100:101]
	v_pk_mul_f32 v[80:81], v[80:81], v[98:99] op_sel_hi:[1,0]
	v_pk_mul_f32 v[88:89], v[88:89], v[92:93]
	v_pk_mul_f32 v[92:93], v[94:95], v[98:99] op_sel_hi:[1,0]
	v_cvt_pk_bf16_f32 v88, v88, v89
	v_mul_f32_e32 v94, 0xbfb8aa3b, v92
	v_mul_f32_e32 v95, 0xbfb8aa3b, v93
	v_exp_f32_e32 v94, v94
	v_exp_f32_e32 v95, v95
	v_pk_mul_f32 v[82:83], v[82:83], v[98:99] op_sel_hi:[1,0]
	v_add_f32_e32 v94, 1.0, v94
	v_add_f32_e32 v95, 1.0, v95
	v_rcp_f32_e32 v94, v94
	v_rcp_f32_e32 v95, v95
	s_nop 0
	v_pk_mul_f32 v[92:93], v[92:93], v[94:95]
	s_nop 0
	v_pk_mul_f32 v[90:91], v[90:91], v[92:93]
	s_nop 0
	v_cvt_pk_bf16_f32 v89, v90, v91
	v_lshl_add_u64 v[90:91], v[96:97], 0, v[120:121]
	global_store_dwordx2 v[90:91], v[88:89], off
	v_mul_f32_e32 v88, 0xbfb8aa3b, v84
	v_mul_f32_e32 v89, 0xbfb8aa3b, v85
	v_exp_f32_e32 v88, v88
	v_exp_f32_e32 v89, v89
	v_add_f32_e32 v88, 1.0, v88
	v_add_f32_e32 v89, 1.0, v89
	v_rcp_f32_e32 v88, v88
	v_rcp_f32_e32 v89, v89
	s_nop 0
	v_pk_mul_f32 v[84:85], v[84:85], v[88:89]
	s_nop 0
	v_pk_mul_f32 v[80:81], v[80:81], v[84:85]
	v_pk_mul_f32 v[84:85], v[86:87], v[98:99] op_sel_hi:[1,0]
	v_cvt_pk_bf16_f32 v80, v80, v81
	v_mul_f32_e32 v86, 0xbfb8aa3b, v84
	v_mul_f32_e32 v87, 0xbfb8aa3b, v85
	v_exp_f32_e32 v86, v86
	v_exp_f32_e32 v87, v87
	v_add_f32_e32 v86, 1.0, v86
	v_add_f32_e32 v87, 1.0, v87
	v_rcp_f32_e32 v86, v86
	v_rcp_f32_e32 v87, v87
	s_nop 0
	v_pk_mul_f32 v[84:85], v[84:85], v[86:87]
	s_nop 0
	v_pk_mul_f32 v[82:83], v[82:83], v[84:85]
	s_nop 0
	v_cvt_pk_bf16_f32 v81, v82, v83
	v_or_b32_e32 v82, 48, v140
	v_ashrrev_i32_e32 v83, 31, v82
	global_store_dwordx2 v[90:91], v[80:81], off offset:128
	v_mad_i64_i32 v[80:81], s[2:3], v82, s78, v[138:139]
	v_mov_b32_e32 v82, v220
	v_mov_b32_e32 v83, v221
	v_mov_b32_e32 v84, v222
	v_mov_b32_e32 v85, v223
	v_mov_b32_e32 v86, v83
	v_mov_b32_e32 v87, v84
	v_mov_b32_e32 v83, v85
	v_pk_add_f32 v[82:83], v[86:87], v[82:83]
	s_nop 0
	v_add_f32_e32 v82, v82, v83
	v_fmamk_f32 v82, v82, 0x3a800000, v184
	v_rsq_f32_e32 v82, v82
	s_nop 0
	v_pk_mul_f32 v[76:77], v[76:77], v[82:83] op_sel_hi:[1,0]
	s_nop 0
	v_mul_f32_e32 v83, 0xbfb8aa3b, v76
	v_exp_f32_e32 v83, v83
	s_nop 0
	v_add_f32_e32 v83, 1.0, v83
	v_rcp_f32_e32 v84, v83
	v_mul_f32_e32 v83, 0xbfb8aa3b, v77
	v_exp_f32_e32 v83, v83
	s_nop 0
	v_add_f32_e32 v83, 1.0, v83
	v_rcp_f32_e32 v85, v83
	v_pk_mul_f32 v[72:73], v[72:73], v[82:83] op_sel_hi:[1,0]
	v_pk_mul_f32 v[74:75], v[74:75], v[82:83] op_sel_hi:[1,0]
	v_pk_mul_f32 v[68:69], v[68:69], v[82:83] op_sel_hi:[1,0]
	v_pk_mul_f32 v[76:77], v[76:77], v[84:85]
	v_pk_mul_f32 v[64:65], v[64:65], v[82:83] op_sel_hi:[1,0]
	v_pk_mul_f32 v[72:73], v[72:73], v[76:77]
	v_pk_mul_f32 v[76:77], v[78:79], v[82:83] op_sel_hi:[1,0]
	v_cvt_pk_bf16_f32 v72, v72, v73
	v_mul_f32_e32 v78, 0xbfb8aa3b, v76
	v_mul_f32_e32 v79, 0xbfb8aa3b, v77
	v_exp_f32_e32 v78, v78
	v_exp_f32_e32 v79, v79
	v_pk_mul_f32 v[66:67], v[66:67], v[82:83] op_sel_hi:[1,0]
	v_add_f32_e32 v78, 1.0, v78
	v_add_f32_e32 v79, 1.0, v79
	v_rcp_f32_e32 v78, v78
	v_rcp_f32_e32 v79, v79
	s_nop 0
	v_pk_mul_f32 v[76:77], v[76:77], v[78:79]
	s_nop 0
	v_pk_mul_f32 v[74:75], v[74:75], v[76:77]
	s_nop 0
	v_cvt_pk_bf16_f32 v73, v74, v75
	v_lshl_add_u64 v[74:75], v[80:81], 0, v[120:121]
	global_store_dwordx2 v[74:75], v[72:73], off
	v_mul_f32_e32 v72, 0xbfb8aa3b, v68
	v_mul_f32_e32 v73, 0xbfb8aa3b, v69
	v_exp_f32_e32 v72, v72
	v_exp_f32_e32 v73, v73
	v_add_f32_e32 v72, 1.0, v72
	v_add_f32_e32 v73, 1.0, v73
	v_rcp_f32_e32 v72, v72
	v_rcp_f32_e32 v73, v73
	s_nop 0
	v_pk_mul_f32 v[68:69], v[68:69], v[72:73]
	s_nop 0
	v_pk_mul_f32 v[64:65], v[64:65], v[68:69]
	v_pk_mul_f32 v[68:69], v[70:71], v[82:83] op_sel_hi:[1,0]
	v_cvt_pk_bf16_f32 v64, v64, v65
	v_mul_f32_e32 v70, 0xbfb8aa3b, v68
	v_mul_f32_e32 v71, 0xbfb8aa3b, v69
	v_exp_f32_e32 v70, v70
	v_exp_f32_e32 v71, v71
	v_add_f32_e32 v70, 1.0, v70
	v_add_f32_e32 v71, 1.0, v71
	v_rcp_f32_e32 v70, v70
	v_rcp_f32_e32 v71, v71
	s_nop 0
	v_pk_mul_f32 v[68:69], v[68:69], v[70:71]
	s_nop 0
	v_pk_mul_f32 v[66:67], v[66:67], v[68:69]
	s_nop 0
	v_cvt_pk_bf16_f32 v65, v66, v67
	v_add_u32_e32 v66, 0x80, v140
	v_ashrrev_i32_e32 v67, 31, v66
	global_store_dwordx2 v[74:75], v[64:65], off offset:128
	v_mad_i64_i32 v[64:65], s[2:3], v66, s78, v[138:139]
	v_mov_b32_e32 v66, v224
	v_mov_b32_e32 v67, v225
	v_mov_b32_e32 v68, v226
	v_mov_b32_e32 v69, v227
	v_mov_b32_e32 v70, v67
	v_mov_b32_e32 v71, v68
	v_mov_b32_e32 v67, v69
	v_pk_add_f32 v[66:67], v[70:71], v[66:67]
	s_nop 0
	v_add_f32_e32 v66, v66, v67
	v_fmamk_f32 v66, v66, 0x3a800000, v184
	v_rsq_f32_e32 v66, v66
	s_nop 0
	v_pk_mul_f32 v[60:61], v[60:61], v[66:67] op_sel_hi:[1,0]
	s_nop 0
	v_mul_f32_e32 v67, 0xbfb8aa3b, v60
	v_exp_f32_e32 v67, v67
	s_nop 0
	v_add_f32_e32 v67, 1.0, v67
	v_rcp_f32_e32 v68, v67
	v_mul_f32_e32 v67, 0xbfb8aa3b, v61
	v_exp_f32_e32 v67, v67
	s_nop 0
	v_add_f32_e32 v67, 1.0, v67
	v_rcp_f32_e32 v69, v67
	v_pk_mul_f32 v[56:57], v[56:57], v[66:67] op_sel_hi:[1,0]
	v_pk_mul_f32 v[58:59], v[58:59], v[66:67] op_sel_hi:[1,0]
	v_pk_mul_f32 v[52:53], v[52:53], v[66:67] op_sel_hi:[1,0]
	v_pk_mul_f32 v[60:61], v[60:61], v[68:69]
	v_pk_mul_f32 v[48:49], v[48:49], v[66:67] op_sel_hi:[1,0]
	v_pk_mul_f32 v[56:57], v[56:57], v[60:61]
	v_pk_mul_f32 v[60:61], v[62:63], v[66:67] op_sel_hi:[1,0]
	v_cvt_pk_bf16_f32 v56, v56, v57
	v_mul_f32_e32 v62, 0xbfb8aa3b, v60
	v_mul_f32_e32 v63, 0xbfb8aa3b, v61
	v_exp_f32_e32 v62, v62
	v_exp_f32_e32 v63, v63
	v_pk_mul_f32 v[50:51], v[50:51], v[66:67] op_sel_hi:[1,0]
	v_add_f32_e32 v62, 1.0, v62
	v_add_f32_e32 v63, 1.0, v63
	v_rcp_f32_e32 v62, v62
	v_rcp_f32_e32 v63, v63
	s_nop 0
	v_pk_mul_f32 v[60:61], v[60:61], v[62:63]
	s_nop 0
	v_pk_mul_f32 v[58:59], v[58:59], v[60:61]
	s_nop 0
	v_cvt_pk_bf16_f32 v57, v58, v59
	v_lshl_add_u64 v[58:59], v[64:65], 0, v[120:121]
	global_store_dwordx2 v[58:59], v[56:57], off
	v_mul_f32_e32 v56, 0xbfb8aa3b, v52
	v_mul_f32_e32 v57, 0xbfb8aa3b, v53
	v_exp_f32_e32 v56, v56
	v_exp_f32_e32 v57, v57
	v_add_f32_e32 v56, 1.0, v56
	v_add_f32_e32 v57, 1.0, v57
	v_rcp_f32_e32 v56, v56
	v_rcp_f32_e32 v57, v57
	s_nop 0
	v_pk_mul_f32 v[52:53], v[52:53], v[56:57]
	s_nop 0
	v_pk_mul_f32 v[48:49], v[48:49], v[52:53]
	v_pk_mul_f32 v[52:53], v[54:55], v[66:67] op_sel_hi:[1,0]
	v_cvt_pk_bf16_f32 v48, v48, v49
	v_mul_f32_e32 v54, 0xbfb8aa3b, v52
	v_mul_f32_e32 v55, 0xbfb8aa3b, v53
	v_exp_f32_e32 v54, v54
	v_exp_f32_e32 v55, v55
	v_add_f32_e32 v54, 1.0, v54
	v_add_f32_e32 v55, 1.0, v55
	v_rcp_f32_e32 v54, v54
	v_rcp_f32_e32 v55, v55
	s_nop 0
	v_pk_mul_f32 v[52:53], v[52:53], v[54:55]
	s_nop 0
	v_pk_mul_f32 v[50:51], v[50:51], v[52:53]
	s_nop 0
	v_cvt_pk_bf16_f32 v49, v50, v51
	v_add_u32_e32 v50, 0x90, v140
	v_ashrrev_i32_e32 v51, 31, v50
	global_store_dwordx2 v[58:59], v[48:49], off offset:128
	v_mad_i64_i32 v[48:49], s[2:3], v50, s78, v[138:139]
	v_mov_b32_e32 v50, v228
	v_mov_b32_e32 v51, v229
	v_mov_b32_e32 v52, v230
	v_mov_b32_e32 v53, v231
	v_mov_b32_e32 v54, v51
	v_mov_b32_e32 v55, v52
	v_mov_b32_e32 v51, v53
	v_pk_add_f32 v[50:51], v[54:55], v[50:51]
	s_nop 0
	v_add_f32_e32 v50, v50, v51
	v_fmamk_f32 v50, v50, 0x3a800000, v184
	v_rsq_f32_e32 v50, v50
	s_nop 0
	v_pk_mul_f32 v[44:45], v[44:45], v[50:51] op_sel_hi:[1,0]
	s_nop 0
	v_mul_f32_e32 v51, 0xbfb8aa3b, v44
	v_exp_f32_e32 v51, v51
	s_nop 0
	v_add_f32_e32 v51, 1.0, v51
	v_rcp_f32_e32 v52, v51
	v_mul_f32_e32 v51, 0xbfb8aa3b, v45
	v_exp_f32_e32 v51, v51
	s_nop 0
	v_add_f32_e32 v51, 1.0, v51
	v_rcp_f32_e32 v53, v51
	v_pk_mul_f32 v[40:41], v[40:41], v[50:51] op_sel_hi:[1,0]
	v_pk_mul_f32 v[42:43], v[42:43], v[50:51] op_sel_hi:[1,0]
	v_pk_mul_f32 v[36:37], v[36:37], v[50:51] op_sel_hi:[1,0]
	v_pk_mul_f32 v[44:45], v[44:45], v[52:53]
	v_pk_mul_f32 v[32:33], v[32:33], v[50:51] op_sel_hi:[1,0]
	v_pk_mul_f32 v[40:41], v[40:41], v[44:45]
	v_pk_mul_f32 v[44:45], v[46:47], v[50:51] op_sel_hi:[1,0]
	v_cvt_pk_bf16_f32 v40, v40, v41
	v_mul_f32_e32 v46, 0xbfb8aa3b, v44
	v_mul_f32_e32 v47, 0xbfb8aa3b, v45
	v_exp_f32_e32 v46, v46
	v_exp_f32_e32 v47, v47
	v_pk_mul_f32 v[34:35], v[34:35], v[50:51] op_sel_hi:[1,0]
	v_add_f32_e32 v46, 1.0, v46
	v_add_f32_e32 v47, 1.0, v47
	v_rcp_f32_e32 v46, v46
	v_rcp_f32_e32 v47, v47
	s_nop 0
	v_pk_mul_f32 v[44:45], v[44:45], v[46:47]
	s_nop 0
	v_pk_mul_f32 v[42:43], v[42:43], v[44:45]
	s_nop 0
	v_cvt_pk_bf16_f32 v41, v42, v43
	v_lshl_add_u64 v[42:43], v[48:49], 0, v[120:121]
	global_store_dwordx2 v[42:43], v[40:41], off
	v_mul_f32_e32 v40, 0xbfb8aa3b, v36
	v_mul_f32_e32 v41, 0xbfb8aa3b, v37
	v_exp_f32_e32 v40, v40
	v_exp_f32_e32 v41, v41
	v_add_f32_e32 v40, 1.0, v40
	v_add_f32_e32 v41, 1.0, v41
	v_rcp_f32_e32 v40, v40
	v_rcp_f32_e32 v41, v41
	s_nop 0
	v_pk_mul_f32 v[36:37], v[36:37], v[40:41]
	s_nop 0
	v_pk_mul_f32 v[32:33], v[32:33], v[36:37]
	v_pk_mul_f32 v[36:37], v[38:39], v[50:51] op_sel_hi:[1,0]
	v_cvt_pk_bf16_f32 v32, v32, v33
	v_mul_f32_e32 v38, 0xbfb8aa3b, v36
	v_mul_f32_e32 v39, 0xbfb8aa3b, v37
	v_exp_f32_e32 v38, v38
	v_exp_f32_e32 v39, v39
	v_add_f32_e32 v38, 1.0, v38
	v_add_f32_e32 v39, 1.0, v39
	v_rcp_f32_e32 v38, v38
	v_rcp_f32_e32 v39, v39
	s_nop 0
	v_pk_mul_f32 v[36:37], v[36:37], v[38:39]
	s_nop 0
	v_pk_mul_f32 v[34:35], v[34:35], v[36:37]
	s_nop 0
	v_cvt_pk_bf16_f32 v33, v34, v35
	v_add_u32_e32 v34, 0xa0, v140
	v_ashrrev_i32_e32 v35, 31, v34
	global_store_dwordx2 v[42:43], v[32:33], off offset:128
	v_mad_i64_i32 v[32:33], s[2:3], v34, s78, v[138:139]
	v_mov_b32_e32 v34, v232
	v_mov_b32_e32 v35, v233
	v_mov_b32_e32 v36, v234
	v_mov_b32_e32 v37, v235
	v_mov_b32_e32 v38, v35
	v_mov_b32_e32 v39, v36
	v_mov_b32_e32 v35, v37
	v_pk_add_f32 v[34:35], v[38:39], v[34:35]
	s_nop 0
	v_add_f32_e32 v34, v34, v35
	v_fmamk_f32 v34, v34, 0x3a800000, v184
	v_rsq_f32_e32 v34, v34
	s_nop 0
	v_pk_mul_f32 v[28:29], v[28:29], v[34:35] op_sel_hi:[1,0]
	s_nop 0
	v_mul_f32_e32 v35, 0xbfb8aa3b, v28
	v_exp_f32_e32 v35, v35
	s_nop 0
	v_add_f32_e32 v35, 1.0, v35
	v_rcp_f32_e32 v36, v35
	v_mul_f32_e32 v35, 0xbfb8aa3b, v29
	v_exp_f32_e32 v35, v35
	s_nop 0
	v_add_f32_e32 v35, 1.0, v35
	v_rcp_f32_e32 v37, v35
	v_pk_mul_f32 v[24:25], v[24:25], v[34:35] op_sel_hi:[1,0]
	v_pk_mul_f32 v[26:27], v[26:27], v[34:35] op_sel_hi:[1,0]
	v_pk_mul_f32 v[20:21], v[20:21], v[34:35] op_sel_hi:[1,0]
	v_pk_mul_f32 v[28:29], v[28:29], v[36:37]
	v_pk_mul_f32 v[16:17], v[16:17], v[34:35] op_sel_hi:[1,0]
	v_pk_mul_f32 v[24:25], v[24:25], v[28:29]
	v_pk_mul_f32 v[28:29], v[30:31], v[34:35] op_sel_hi:[1,0]
	v_cvt_pk_bf16_f32 v24, v24, v25
	v_mul_f32_e32 v30, 0xbfb8aa3b, v28
	v_mul_f32_e32 v31, 0xbfb8aa3b, v29
	v_exp_f32_e32 v30, v30
	v_exp_f32_e32 v31, v31
	v_pk_mul_f32 v[18:19], v[18:19], v[34:35] op_sel_hi:[1,0]
	v_add_f32_e32 v30, 1.0, v30
	v_add_f32_e32 v31, 1.0, v31
	v_rcp_f32_e32 v30, v30
	v_rcp_f32_e32 v31, v31
	s_nop 0
	v_pk_mul_f32 v[28:29], v[28:29], v[30:31]
	s_nop 0
	v_pk_mul_f32 v[26:27], v[26:27], v[28:29]
	s_nop 0
	v_cvt_pk_bf16_f32 v25, v26, v27
	v_lshl_add_u64 v[26:27], v[32:33], 0, v[120:121]
	global_store_dwordx2 v[26:27], v[24:25], off
	v_mul_f32_e32 v24, 0xbfb8aa3b, v20
	v_mul_f32_e32 v25, 0xbfb8aa3b, v21
	v_exp_f32_e32 v24, v24
	v_exp_f32_e32 v25, v25
	v_add_f32_e32 v24, 1.0, v24
	v_add_f32_e32 v25, 1.0, v25
	v_rcp_f32_e32 v24, v24
	v_rcp_f32_e32 v25, v25
	s_nop 0
	v_pk_mul_f32 v[20:21], v[20:21], v[24:25]
	s_nop 0
	v_pk_mul_f32 v[16:17], v[16:17], v[20:21]
	v_pk_mul_f32 v[20:21], v[22:23], v[34:35] op_sel_hi:[1,0]
	v_cvt_pk_bf16_f32 v16, v16, v17
	v_mul_f32_e32 v22, 0xbfb8aa3b, v20
	v_mul_f32_e32 v23, 0xbfb8aa3b, v21
	v_exp_f32_e32 v22, v22
	v_exp_f32_e32 v23, v23
	v_add_f32_e32 v22, 1.0, v22
	v_add_f32_e32 v23, 1.0, v23
	v_rcp_f32_e32 v22, v22
	v_rcp_f32_e32 v23, v23
	s_nop 0
	v_pk_mul_f32 v[20:21], v[20:21], v[22:23]
	s_nop 0
	v_pk_mul_f32 v[18:19], v[18:19], v[20:21]
	s_nop 0
	v_cvt_pk_bf16_f32 v17, v18, v19
	v_add_u32_e32 v18, 0xb0, v140
	v_ashrrev_i32_e32 v19, 31, v18
	global_store_dwordx2 v[26:27], v[16:17], off offset:128
	v_mad_i64_i32 v[16:17], s[2:3], v18, s78, v[138:139]
	v_mov_b32_e32 v18, v236
	v_mov_b32_e32 v19, v237
	v_mov_b32_e32 v20, v238
	v_mov_b32_e32 v21, v239
	s_mov_b64 s[2:3], -1
	v_mov_b32_e32 v22, v19
	v_mov_b32_e32 v23, v20
	v_mov_b32_e32 v19, v21
	v_pk_add_f32 v[18:19], v[22:23], v[18:19]
	s_nop 0
	v_add_f32_e32 v18, v18, v19
	v_fmamk_f32 v18, v18, 0x3a800000, v184
	v_rsq_f32_e32 v18, v18
	s_nop 0
	v_pk_mul_f32 v[12:13], v[12:13], v[18:19] op_sel_hi:[1,0]
	s_nop 0
	v_mul_f32_e32 v19, 0xbfb8aa3b, v12
	v_exp_f32_e32 v19, v19
	s_nop 0
	v_add_f32_e32 v19, 1.0, v19
	v_rcp_f32_e32 v20, v19
	v_mul_f32_e32 v19, 0xbfb8aa3b, v13
	v_exp_f32_e32 v19, v19
	s_nop 0
	v_add_f32_e32 v19, 1.0, v19
	v_rcp_f32_e32 v21, v19
	v_pk_mul_f32 v[8:9], v[8:9], v[18:19] op_sel_hi:[1,0]
	v_pk_mul_f32 v[10:11], v[10:11], v[18:19] op_sel_hi:[1,0]
	v_pk_mul_f32 v[4:5], v[4:5], v[18:19] op_sel_hi:[1,0]
	v_pk_mul_f32 v[12:13], v[12:13], v[20:21]
	v_pk_mul_f32 v[0:1], v[0:1], v[18:19] op_sel_hi:[1,0]
	v_pk_mul_f32 v[8:9], v[8:9], v[12:13]
	v_pk_mul_f32 v[12:13], v[14:15], v[18:19] op_sel_hi:[1,0]
	v_cvt_pk_bf16_f32 v8, v8, v9
	v_mul_f32_e32 v14, 0xbfb8aa3b, v12
	v_mul_f32_e32 v15, 0xbfb8aa3b, v13
	v_exp_f32_e32 v14, v14
	v_exp_f32_e32 v15, v15
	v_pk_mul_f32 v[2:3], v[2:3], v[18:19] op_sel_hi:[1,0]
	v_add_f32_e32 v14, 1.0, v14
	v_add_f32_e32 v15, 1.0, v15
	v_rcp_f32_e32 v14, v14
	v_rcp_f32_e32 v15, v15
	s_nop 0
	v_pk_mul_f32 v[12:13], v[12:13], v[14:15]
	s_nop 0
	v_pk_mul_f32 v[10:11], v[10:11], v[12:13]
	s_nop 0
	v_cvt_pk_bf16_f32 v9, v10, v11
	v_lshl_add_u64 v[10:11], v[16:17], 0, v[120:121]
	global_store_dwordx2 v[10:11], v[8:9], off
	v_mul_f32_e32 v8, 0xbfb8aa3b, v4
	v_mul_f32_e32 v9, 0xbfb8aa3b, v5
	v_exp_f32_e32 v8, v8
	v_exp_f32_e32 v9, v9
	v_add_f32_e32 v8, 1.0, v8
	v_add_f32_e32 v9, 1.0, v9
	v_rcp_f32_e32 v8, v8
	v_rcp_f32_e32 v9, v9
	s_nop 0
	v_pk_mul_f32 v[4:5], v[4:5], v[8:9]
	s_nop 0
	v_pk_mul_f32 v[0:1], v[0:1], v[4:5]
	v_pk_mul_f32 v[4:5], v[6:7], v[18:19] op_sel_hi:[1,0]
	v_cvt_pk_bf16_f32 v0, v0, v1
	v_mul_f32_e32 v6, 0xbfb8aa3b, v4
	v_mul_f32_e32 v7, 0xbfb8aa3b, v5
	v_exp_f32_e32 v6, v6
	v_exp_f32_e32 v7, v7
	v_add_f32_e32 v6, 1.0, v6
	v_add_f32_e32 v7, 1.0, v7
	v_rcp_f32_e32 v6, v6
	v_rcp_f32_e32 v7, v7
	s_nop 0
	v_pk_mul_f32 v[4:5], v[4:5], v[6:7]
	s_nop 0
	v_pk_mul_f32 v[2:3], v[2:3], v[4:5]
	s_nop 0
	v_cvt_pk_bf16_f32 v1, v2, v3
	global_store_dwordx2 v[10:11], v[0:1], off offset:128
	s_cbranch_vccnz .LBB0_307
	s_andn2_b64 vcc, exec, s[40:41]
	s_cbranch_vccnz .LBB0_306
	s_barrier
	s_branch .LBB0_306

.LBB0_1308:
	v_lshl_add_u32 v140, s58, 8, v142
	v_ashrrev_i32_e32 v141, 31, v140
	v_lshl_add_u64 v[156:157], v[140:141], 4, s[44:45]
	global_load_dwordx4 v[212:215], v[156:157], off offset:256
	global_load_dwordx4 v[216:219], v[156:157], off offset:512
	global_load_dwordx4 v[220:223], v[156:157], off offset:768
	global_load_dwordx4 v[224:227], v[156:157], off offset:2048
	global_load_dwordx4 v[228:231], v[156:157], off offset:2304
	global_load_dwordx4 v[232:235], v[156:157], off offset:2560
	global_load_dwordx4 v[236:239], v[156:157], off offset:2816
	global_load_dwordx4 v[156:159], v[156:157], off
	v_lshl_or_b32 v164, s33, 8, v154
	v_mov_b64_e32 v[138:139], s[42:43]
	v_mad_i64_i32 v[160:161], s[2:3], v140, s78, v[138:139]
	s_andn2_b64 vcc, exec, s[38:39]
	s_waitcnt vmcnt(0)
	v_mov_b32_e32 v162, v157
	v_mov_b32_e32 v163, v158
	v_mov_b32_e32 v157, v159
	v_pk_add_f32 v[156:157], v[162:163], v[156:157]
	s_nop 0
	v_add_f32_e32 v141, v156, v157
	v_fmamk_f32 v141, v141, 0x3a800000, v184
	v_rsq_f32_e32 v156, v141
	s_nop 0
	v_pk_mul_f32 v[124:125], v[124:125], v[156:157] op_sel_hi:[1,0]
	s_nop 0
	v_mul_f32_e32 v141, 0xbfb8aa3b, v124
	v_exp_f32_e32 v141, v141
	v_pk_mul_f32 v[120:121], v[120:121], v[156:157] op_sel_hi:[1,0]
	v_pk_mul_f32 v[122:123], v[122:123], v[156:157] op_sel_hi:[1,0]
	v_pk_mul_f32 v[116:117], v[116:117], v[156:157] op_sel_hi:[1,0]
	v_add_f32_e32 v141, 1.0, v141
	v_rcp_f32_e32 v158, v141
	v_mul_f32_e32 v141, 0xbfb8aa3b, v125
	v_exp_f32_e32 v141, v141
	v_pk_mul_f32 v[112:113], v[112:113], v[156:157] op_sel_hi:[1,0]
	v_pk_mul_f32 v[114:115], v[114:115], v[156:157] op_sel_hi:[1,0]
	v_add_f32_e32 v141, 1.0, v141
	v_rcp_f32_e32 v159, v141
	s_nop 0
	v_pk_mul_f32 v[124:125], v[124:125], v[158:159]
	s_nop 0
	v_pk_mul_f32 v[120:121], v[120:121], v[124:125]
	v_pk_mul_f32 v[124:125], v[126:127], v[156:157] op_sel_hi:[1,0]
	s_nop 0
	v_mul_f32_e32 v126, 0xbfb8aa3b, v124
	v_mul_f32_e32 v127, 0xbfb8aa3b, v125
	v_exp_f32_e32 v126, v126
	v_exp_f32_e32 v127, v127
	v_add_f32_e32 v126, 1.0, v126
	v_add_f32_e32 v127, 1.0, v127
	v_rcp_f32_e32 v126, v126
	v_rcp_f32_e32 v127, v127
	s_nop 0
	v_pk_mul_f32 v[124:125], v[124:125], v[126:127]
	s_nop 0
	v_pk_mul_f32 v[122:123], v[122:123], v[124:125]
	v_cvt_pk_bf16_f32 v124, v120, v121
	v_ashrrev_i32_e32 v120, 1, v164
	v_ashrrev_i32_e32 v121, 31, v120
	v_lshlrev_b64 v[120:121], 1, v[120:121]
	v_cvt_pk_bf16_f32 v125, v122, v123
	v_lshl_add_u64 v[122:123], v[160:161], 0, v[120:121]
	global_store_dwordx2 v[122:123], v[124:125], off
	v_mul_f32_e32 v124, 0xbfb8aa3b, v116
	v_mul_f32_e32 v125, 0xbfb8aa3b, v117
	v_exp_f32_e32 v124, v124
	v_exp_f32_e32 v125, v125
	v_add_f32_e32 v124, 1.0, v124
	v_add_f32_e32 v125, 1.0, v125
	v_rcp_f32_e32 v124, v124
	v_rcp_f32_e32 v125, v125
	s_nop 0
	v_pk_mul_f32 v[116:117], v[116:117], v[124:125]
	s_nop 0
	v_pk_mul_f32 v[112:113], v[112:113], v[116:117]
	v_pk_mul_f32 v[116:117], v[118:119], v[156:157] op_sel_hi:[1,0]
	v_cvt_pk_bf16_f32 v112, v112, v113
	v_mul_f32_e32 v118, 0xbfb8aa3b, v116
	v_mul_f32_e32 v119, 0xbfb8aa3b, v117
	v_exp_f32_e32 v118, v118
	v_exp_f32_e32 v119, v119
	v_add_f32_e32 v118, 1.0, v118
	v_add_f32_e32 v119, 1.0, v119
	v_rcp_f32_e32 v118, v118
	v_rcp_f32_e32 v119, v119
	s_nop 0
	v_pk_mul_f32 v[116:117], v[116:117], v[118:119]
	s_nop 0
	v_pk_mul_f32 v[114:115], v[114:115], v[116:117]
	s_nop 0
	v_cvt_pk_bf16_f32 v113, v114, v115
	v_or_b32_e32 v114, 16, v140
	v_ashrrev_i32_e32 v115, 31, v114
	global_store_dwordx2 v[122:123], v[112:113], off offset:128
	v_mad_i64_i32 v[112:113], s[2:3], v114, s78, v[138:139]
	v_mov_b32_e32 v114, v212
	v_mov_b32_e32 v115, v213
	v_mov_b32_e32 v116, v214
	v_mov_b32_e32 v117, v215
	v_mov_b32_e32 v118, v115
	v_mov_b32_e32 v119, v116
	v_mov_b32_e32 v115, v117
	v_pk_add_f32 v[114:115], v[118:119], v[114:115]
	s_nop 0
	v_add_f32_e32 v114, v114, v115
	v_fmamk_f32 v114, v114, 0x3a800000, v184
	v_rsq_f32_e32 v114, v114
	s_nop 0
	v_pk_mul_f32 v[108:109], v[108:109], v[114:115] op_sel_hi:[1,0]
	s_nop 0
	v_mul_f32_e32 v115, 0xbfb8aa3b, v108
	v_exp_f32_e32 v115, v115
	s_nop 0
	v_add_f32_e32 v115, 1.0, v115
	v_rcp_f32_e32 v116, v115
	v_mul_f32_e32 v115, 0xbfb8aa3b, v109
	v_exp_f32_e32 v115, v115
	s_nop 0
	v_add_f32_e32 v115, 1.0, v115
	v_rcp_f32_e32 v117, v115
	v_pk_mul_f32 v[104:105], v[104:105], v[114:115] op_sel_hi:[1,0]
	v_pk_mul_f32 v[106:107], v[106:107], v[114:115] op_sel_hi:[1,0]
	v_pk_mul_f32 v[100:101], v[100:101], v[114:115] op_sel_hi:[1,0]
	v_pk_mul_f32 v[108:109], v[108:109], v[116:117]
	v_pk_mul_f32 v[96:97], v[96:97], v[114:115] op_sel_hi:[1,0]
	v_pk_mul_f32 v[104:105], v[104:105], v[108:109]
	v_pk_mul_f32 v[108:109], v[110:111], v[114:115] op_sel_hi:[1,0]
	v_cvt_pk_bf16_f32 v104, v104, v105
	v_mul_f32_e32 v110, 0xbfb8aa3b, v108
	v_mul_f32_e32 v111, 0xbfb8aa3b, v109
	v_exp_f32_e32 v110, v110
	v_exp_f32_e32 v111, v111
	v_pk_mul_f32 v[98:99], v[98:99], v[114:115] op_sel_hi:[1,0]
	v_add_f32_e32 v110, 1.0, v110
	v_add_f32_e32 v111, 1.0, v111
	v_rcp_f32_e32 v110, v110
	v_rcp_f32_e32 v111, v111
	s_nop 0
	v_pk_mul_f32 v[108:109], v[108:109], v[110:111]
	s_nop 0
	v_pk_mul_f32 v[106:107], v[106:107], v[108:109]
	s_nop 0
	v_cvt_pk_bf16_f32 v105, v106, v107
	v_lshl_add_u64 v[106:107], v[112:113], 0, v[120:121]
	global_store_dwordx2 v[106:107], v[104:105], off
	v_mul_f32_e32 v104, 0xbfb8aa3b, v100
	v_mul_f32_e32 v105, 0xbfb8aa3b, v101
	v_exp_f32_e32 v104, v104
	v_exp_f32_e32 v105, v105
	v_add_f32_e32 v104, 1.0, v104
	v_add_f32_e32 v105, 1.0, v105
	v_rcp_f32_e32 v104, v104
	v_rcp_f32_e32 v105, v105
	s_nop 0
	v_pk_mul_f32 v[100:101], v[100:101], v[104:105]
	s_nop 0
	v_pk_mul_f32 v[96:97], v[96:97], v[100:101]
	v_pk_mul_f32 v[100:101], v[102:103], v[114:115] op_sel_hi:[1,0]
	v_cvt_pk_bf16_f32 v96, v96, v97
	v_mul_f32_e32 v102, 0xbfb8aa3b, v100
	v_mul_f32_e32 v103, 0xbfb8aa3b, v101
	v_exp_f32_e32 v102, v102
	v_exp_f32_e32 v103, v103
	v_add_f32_e32 v102, 1.0, v102
	v_add_f32_e32 v103, 1.0, v103
	v_rcp_f32_e32 v102, v102
	v_rcp_f32_e32 v103, v103
	s_nop 0
	v_pk_mul_f32 v[100:101], v[100:101], v[102:103]
	s_nop 0
	v_pk_mul_f32 v[98:99], v[98:99], v[100:101]
	s_nop 0
	v_cvt_pk_bf16_f32 v97, v98, v99
	v_or_b32_e32 v98, 32, v140
	v_ashrrev_i32_e32 v99, 31, v98
	global_store_dwordx2 v[106:107], v[96:97], off offset:128
	v_mad_i64_i32 v[96:97], s[2:3], v98, s78, v[138:139]
	v_mov_b32_e32 v98, v216
	v_mov_b32_e32 v99, v217
	v_mov_b32_e32 v100, v218
	v_mov_b32_e32 v101, v219
	v_mov_b32_e32 v102, v99
	v_mov_b32_e32 v103, v100
	v_mov_b32_e32 v99, v101
	v_pk_add_f32 v[98:99], v[102:103], v[98:99]
	s_nop 0
	v_add_f32_e32 v98, v98, v99
	v_fmamk_f32 v98, v98, 0x3a800000, v184
	v_rsq_f32_e32 v98, v98
	s_nop 0
	v_pk_mul_f32 v[92:93], v[92:93], v[98:99] op_sel_hi:[1,0]
	s_nop 0
	v_mul_f32_e32 v99, 0xbfb8aa3b, v92
	v_exp_f32_e32 v99, v99
	s_nop 0
	v_add_f32_e32 v99, 1.0, v99
	v_rcp_f32_e32 v100, v99
	v_mul_f32_e32 v99, 0xbfb8aa3b, v93
	v_exp_f32_e32 v99, v99
	s_nop 0
	v_add_f32_e32 v99, 1.0, v99
	v_rcp_f32_e32 v101, v99
	v_pk_mul_f32 v[88:89], v[88:89], v[98:99] op_sel_hi:[1,0]
	v_pk_mul_f32 v[90:91], v[90:91], v[98:99] op_sel_hi:[1,0]
	v_pk_mul_f32 v[84:85], v[84:85], v[98:99] op_sel_hi:[1,0]
	v_pk_mul_f32 v[92:93], v[92:93], v[100:101]
	v_pk_mul_f32 v[80:81], v[80:81], v[98:99] op_sel_hi:[1,0]
	v_pk_mul_f32 v[88:89], v[88:89], v[92:93]
	v_pk_mul_f32 v[92:93], v[94:95], v[98:99] op_sel_hi:[1,0]
	v_cvt_pk_bf16_f32 v88, v88, v89
	v_mul_f32_e32 v94, 0xbfb8aa3b, v92
	v_mul_f32_e32 v95, 0xbfb8aa3b, v93
	v_exp_f32_e32 v94, v94
	v_exp_f32_e32 v95, v95
	v_pk_mul_f32 v[82:83], v[82:83], v[98:99] op_sel_hi:[1,0]
	v_add_f32_e32 v94, 1.0, v94
	v_add_f32_e32 v95, 1.0, v95
	v_rcp_f32_e32 v94, v94
	v_rcp_f32_e32 v95, v95
	s_nop 0
	v_pk_mul_f32 v[92:93], v[92:93], v[94:95]
	s_nop 0
	v_pk_mul_f32 v[90:91], v[90:91], v[92:93]
	s_nop 0
	v_cvt_pk_bf16_f32 v89, v90, v91
	v_lshl_add_u64 v[90:91], v[96:97], 0, v[120:121]
	global_store_dwordx2 v[90:91], v[88:89], off
	v_mul_f32_e32 v88, 0xbfb8aa3b, v84
	v_mul_f32_e32 v89, 0xbfb8aa3b, v85
	v_exp_f32_e32 v88, v88
	v_exp_f32_e32 v89, v89
	v_add_f32_e32 v88, 1.0, v88
	v_add_f32_e32 v89, 1.0, v89
	v_rcp_f32_e32 v88, v88
	v_rcp_f32_e32 v89, v89
	s_nop 0
	v_pk_mul_f32 v[84:85], v[84:85], v[88:89]
	s_nop 0
	v_pk_mul_f32 v[80:81], v[80:81], v[84:85]
	v_pk_mul_f32 v[84:85], v[86:87], v[98:99] op_sel_hi:[1,0]
	v_cvt_pk_bf16_f32 v80, v80, v81
	v_mul_f32_e32 v86, 0xbfb8aa3b, v84
	v_mul_f32_e32 v87, 0xbfb8aa3b, v85
	v_exp_f32_e32 v86, v86
	v_exp_f32_e32 v87, v87
	v_add_f32_e32 v86, 1.0, v86
	v_add_f32_e32 v87, 1.0, v87
	v_rcp_f32_e32 v86, v86
	v_rcp_f32_e32 v87, v87
	s_nop 0
	v_pk_mul_f32 v[84:85], v[84:85], v[86:87]
	s_nop 0
	v_pk_mul_f32 v[82:83], v[82:83], v[84:85]
	s_nop 0
	v_cvt_pk_bf16_f32 v81, v82, v83
	v_or_b32_e32 v82, 48, v140
	v_ashrrev_i32_e32 v83, 31, v82
	global_store_dwordx2 v[90:91], v[80:81], off offset:128
	v_mad_i64_i32 v[80:81], s[2:3], v82, s78, v[138:139]
	v_mov_b32_e32 v82, v220
	v_mov_b32_e32 v83, v221
	v_mov_b32_e32 v84, v222
	v_mov_b32_e32 v85, v223
	v_mov_b32_e32 v86, v83
	v_mov_b32_e32 v87, v84
	v_mov_b32_e32 v83, v85
	v_pk_add_f32 v[82:83], v[86:87], v[82:83]
	s_nop 0
	v_add_f32_e32 v82, v82, v83
	v_fmamk_f32 v82, v82, 0x3a800000, v184
	v_rsq_f32_e32 v82, v82
	s_nop 0
	v_pk_mul_f32 v[76:77], v[76:77], v[82:83] op_sel_hi:[1,0]
	s_nop 0
	v_mul_f32_e32 v83, 0xbfb8aa3b, v76
	v_exp_f32_e32 v83, v83
	s_nop 0
	v_add_f32_e32 v83, 1.0, v83
	v_rcp_f32_e32 v84, v83
	v_mul_f32_e32 v83, 0xbfb8aa3b, v77
	v_exp_f32_e32 v83, v83
	s_nop 0
	v_add_f32_e32 v83, 1.0, v83
	v_rcp_f32_e32 v85, v83
	v_pk_mul_f32 v[72:73], v[72:73], v[82:83] op_sel_hi:[1,0]
	v_pk_mul_f32 v[74:75], v[74:75], v[82:83] op_sel_hi:[1,0]
	v_pk_mul_f32 v[68:69], v[68:69], v[82:83] op_sel_hi:[1,0]
	v_pk_mul_f32 v[76:77], v[76:77], v[84:85]
	v_pk_mul_f32 v[64:65], v[64:65], v[82:83] op_sel_hi:[1,0]
	v_pk_mul_f32 v[72:73], v[72:73], v[76:77]
	v_pk_mul_f32 v[76:77], v[78:79], v[82:83] op_sel_hi:[1,0]
	v_cvt_pk_bf16_f32 v72, v72, v73
	v_mul_f32_e32 v78, 0xbfb8aa3b, v76
	v_mul_f32_e32 v79, 0xbfb8aa3b, v77
	v_exp_f32_e32 v78, v78
	v_exp_f32_e32 v79, v79
	v_pk_mul_f32 v[66:67], v[66:67], v[82:83] op_sel_hi:[1,0]
	v_add_f32_e32 v78, 1.0, v78
	v_add_f32_e32 v79, 1.0, v79
	v_rcp_f32_e32 v78, v78
	v_rcp_f32_e32 v79, v79
	s_nop 0
	v_pk_mul_f32 v[76:77], v[76:77], v[78:79]
	s_nop 0
	v_pk_mul_f32 v[74:75], v[74:75], v[76:77]
	s_nop 0
	v_cvt_pk_bf16_f32 v73, v74, v75
	v_lshl_add_u64 v[74:75], v[80:81], 0, v[120:121]
	global_store_dwordx2 v[74:75], v[72:73], off
	v_mul_f32_e32 v72, 0xbfb8aa3b, v68
	v_mul_f32_e32 v73, 0xbfb8aa3b, v69
	v_exp_f32_e32 v72, v72
	v_exp_f32_e32 v73, v73
	v_add_f32_e32 v72, 1.0, v72
	v_add_f32_e32 v73, 1.0, v73
	v_rcp_f32_e32 v72, v72
	v_rcp_f32_e32 v73, v73
	s_nop 0
	v_pk_mul_f32 v[68:69], v[68:69], v[72:73]
	s_nop 0
	v_pk_mul_f32 v[64:65], v[64:65], v[68:69]
	v_pk_mul_f32 v[68:69], v[70:71], v[82:83] op_sel_hi:[1,0]
	v_cvt_pk_bf16_f32 v64, v64, v65
	v_mul_f32_e32 v70, 0xbfb8aa3b, v68
	v_mul_f32_e32 v71, 0xbfb8aa3b, v69
	v_exp_f32_e32 v70, v70
	v_exp_f32_e32 v71, v71
	v_add_f32_e32 v70, 1.0, v70
	v_add_f32_e32 v71, 1.0, v71
	v_rcp_f32_e32 v70, v70
	v_rcp_f32_e32 v71, v71
	s_nop 0
	v_pk_mul_f32 v[68:69], v[68:69], v[70:71]
	s_nop 0
	v_pk_mul_f32 v[66:67], v[66:67], v[68:69]
	s_nop 0
	v_cvt_pk_bf16_f32 v65, v66, v67
	v_add_u32_e32 v66, 0x80, v140
	v_ashrrev_i32_e32 v67, 31, v66
	global_store_dwordx2 v[74:75], v[64:65], off offset:128
	v_mad_i64_i32 v[64:65], s[2:3], v66, s78, v[138:139]
	v_mov_b32_e32 v66, v224
	v_mov_b32_e32 v67, v225
	v_mov_b32_e32 v68, v226
	v_mov_b32_e32 v69, v227
	v_mov_b32_e32 v70, v67
	v_mov_b32_e32 v71, v68
	v_mov_b32_e32 v67, v69
	v_pk_add_f32 v[66:67], v[70:71], v[66:67]
	s_nop 0
	v_add_f32_e32 v66, v66, v67
	v_fmamk_f32 v66, v66, 0x3a800000, v184
	v_rsq_f32_e32 v66, v66
	s_nop 0
	v_pk_mul_f32 v[60:61], v[60:61], v[66:67] op_sel_hi:[1,0]
	s_nop 0
	v_mul_f32_e32 v67, 0xbfb8aa3b, v60
	v_exp_f32_e32 v67, v67
	s_nop 0
	v_add_f32_e32 v67, 1.0, v67
	v_rcp_f32_e32 v68, v67
	v_mul_f32_e32 v67, 0xbfb8aa3b, v61
	v_exp_f32_e32 v67, v67
	s_nop 0
	v_add_f32_e32 v67, 1.0, v67
	v_rcp_f32_e32 v69, v67
	v_pk_mul_f32 v[56:57], v[56:57], v[66:67] op_sel_hi:[1,0]
	v_pk_mul_f32 v[58:59], v[58:59], v[66:67] op_sel_hi:[1,0]
	v_pk_mul_f32 v[52:53], v[52:53], v[66:67] op_sel_hi:[1,0]
	v_pk_mul_f32 v[60:61], v[60:61], v[68:69]
	v_pk_mul_f32 v[48:49], v[48:49], v[66:67] op_sel_hi:[1,0]
	v_pk_mul_f32 v[56:57], v[56:57], v[60:61]
	v_pk_mul_f32 v[60:61], v[62:63], v[66:67] op_sel_hi:[1,0]
	v_cvt_pk_bf16_f32 v56, v56, v57
	v_mul_f32_e32 v62, 0xbfb8aa3b, v60
	v_mul_f32_e32 v63, 0xbfb8aa3b, v61
	v_exp_f32_e32 v62, v62
	v_exp_f32_e32 v63, v63
	v_pk_mul_f32 v[50:51], v[50:51], v[66:67] op_sel_hi:[1,0]
	v_add_f32_e32 v62, 1.0, v62
	v_add_f32_e32 v63, 1.0, v63
	v_rcp_f32_e32 v62, v62
	v_rcp_f32_e32 v63, v63
	s_nop 0
	v_pk_mul_f32 v[60:61], v[60:61], v[62:63]
	s_nop 0
	v_pk_mul_f32 v[58:59], v[58:59], v[60:61]
	s_nop 0
	v_cvt_pk_bf16_f32 v57, v58, v59
	v_lshl_add_u64 v[58:59], v[64:65], 0, v[120:121]
	global_store_dwordx2 v[58:59], v[56:57], off
	v_mul_f32_e32 v56, 0xbfb8aa3b, v52
	v_mul_f32_e32 v57, 0xbfb8aa3b, v53
	v_exp_f32_e32 v56, v56
	v_exp_f32_e32 v57, v57
	v_add_f32_e32 v56, 1.0, v56
	v_add_f32_e32 v57, 1.0, v57
	v_rcp_f32_e32 v56, v56
	v_rcp_f32_e32 v57, v57
	s_nop 0
	v_pk_mul_f32 v[52:53], v[52:53], v[56:57]
	s_nop 0
	v_pk_mul_f32 v[48:49], v[48:49], v[52:53]
	v_pk_mul_f32 v[52:53], v[54:55], v[66:67] op_sel_hi:[1,0]
	v_cvt_pk_bf16_f32 v48, v48, v49
	v_mul_f32_e32 v54, 0xbfb8aa3b, v52
	v_mul_f32_e32 v55, 0xbfb8aa3b, v53
	v_exp_f32_e32 v54, v54
	v_exp_f32_e32 v55, v55
	v_add_f32_e32 v54, 1.0, v54
	v_add_f32_e32 v55, 1.0, v55
	v_rcp_f32_e32 v54, v54
	v_rcp_f32_e32 v55, v55
	s_nop 0
	v_pk_mul_f32 v[52:53], v[52:53], v[54:55]
	s_nop 0
	v_pk_mul_f32 v[50:51], v[50:51], v[52:53]
	s_nop 0
	v_cvt_pk_bf16_f32 v49, v50, v51
	v_add_u32_e32 v50, 0x90, v140
	v_ashrrev_i32_e32 v51, 31, v50
	global_store_dwordx2 v[58:59], v[48:49], off offset:128
	v_mad_i64_i32 v[48:49], s[2:3], v50, s78, v[138:139]
	v_mov_b32_e32 v50, v228
	v_mov_b32_e32 v51, v229
	v_mov_b32_e32 v52, v230
	v_mov_b32_e32 v53, v231
	v_mov_b32_e32 v54, v51
	v_mov_b32_e32 v55, v52
	v_mov_b32_e32 v51, v53
	v_pk_add_f32 v[50:51], v[54:55], v[50:51]
	s_nop 0
	v_add_f32_e32 v50, v50, v51
	v_fmamk_f32 v50, v50, 0x3a800000, v184
	v_rsq_f32_e32 v50, v50
	s_nop 0
	v_pk_mul_f32 v[44:45], v[44:45], v[50:51] op_sel_hi:[1,0]
	s_nop 0
	v_mul_f32_e32 v51, 0xbfb8aa3b, v44
	v_exp_f32_e32 v51, v51
	s_nop 0
	v_add_f32_e32 v51, 1.0, v51
	v_rcp_f32_e32 v52, v51
	v_mul_f32_e32 v51, 0xbfb8aa3b, v45
	v_exp_f32_e32 v51, v51
	s_nop 0
	v_add_f32_e32 v51, 1.0, v51
	v_rcp_f32_e32 v53, v51
	v_pk_mul_f32 v[40:41], v[40:41], v[50:51] op_sel_hi:[1,0]
	v_pk_mul_f32 v[42:43], v[42:43], v[50:51] op_sel_hi:[1,0]
	v_pk_mul_f32 v[36:37], v[36:37], v[50:51] op_sel_hi:[1,0]
	v_pk_mul_f32 v[44:45], v[44:45], v[52:53]
	v_pk_mul_f32 v[32:33], v[32:33], v[50:51] op_sel_hi:[1,0]
	v_pk_mul_f32 v[40:41], v[40:41], v[44:45]
	v_pk_mul_f32 v[44:45], v[46:47], v[50:51] op_sel_hi:[1,0]
	v_cvt_pk_bf16_f32 v40, v40, v41
	v_mul_f32_e32 v46, 0xbfb8aa3b, v44
	v_mul_f32_e32 v47, 0xbfb8aa3b, v45
	v_exp_f32_e32 v46, v46
	v_exp_f32_e32 v47, v47
	v_pk_mul_f32 v[34:35], v[34:35], v[50:51] op_sel_hi:[1,0]
	v_add_f32_e32 v46, 1.0, v46
	v_add_f32_e32 v47, 1.0, v47
	v_rcp_f32_e32 v46, v46
	v_rcp_f32_e32 v47, v47
	s_nop 0
	v_pk_mul_f32 v[44:45], v[44:45], v[46:47]
	s_nop 0
	v_pk_mul_f32 v[42:43], v[42:43], v[44:45]
	s_nop 0
	v_cvt_pk_bf16_f32 v41, v42, v43
	v_lshl_add_u64 v[42:43], v[48:49], 0, v[120:121]
	global_store_dwordx2 v[42:43], v[40:41], off
	v_mul_f32_e32 v40, 0xbfb8aa3b, v36
	v_mul_f32_e32 v41, 0xbfb8aa3b, v37
	v_exp_f32_e32 v40, v40
	v_exp_f32_e32 v41, v41
	v_add_f32_e32 v40, 1.0, v40
	v_add_f32_e32 v41, 1.0, v41
	v_rcp_f32_e32 v40, v40
	v_rcp_f32_e32 v41, v41
	s_nop 0
	v_pk_mul_f32 v[36:37], v[36:37], v[40:41]
	s_nop 0
	v_pk_mul_f32 v[32:33], v[32:33], v[36:37]
	v_pk_mul_f32 v[36:37], v[38:39], v[50:51] op_sel_hi:[1,0]
	v_cvt_pk_bf16_f32 v32, v32, v33
	v_mul_f32_e32 v38, 0xbfb8aa3b, v36
	v_mul_f32_e32 v39, 0xbfb8aa3b, v37
	v_exp_f32_e32 v38, v38
	v_exp_f32_e32 v39, v39
	v_add_f32_e32 v38, 1.0, v38
	v_add_f32_e32 v39, 1.0, v39
	v_rcp_f32_e32 v38, v38
	v_rcp_f32_e32 v39, v39
	s_nop 0
	v_pk_mul_f32 v[36:37], v[36:37], v[38:39]
	s_nop 0
	v_pk_mul_f32 v[34:35], v[34:35], v[36:37]
	s_nop 0
	v_cvt_pk_bf16_f32 v33, v34, v35
	v_add_u32_e32 v34, 0xa0, v140
	v_ashrrev_i32_e32 v35, 31, v34
	global_store_dwordx2 v[42:43], v[32:33], off offset:128
	v_mad_i64_i32 v[32:33], s[2:3], v34, s78, v[138:139]
	v_mov_b32_e32 v34, v232
	v_mov_b32_e32 v35, v233
	v_mov_b32_e32 v36, v234
	v_mov_b32_e32 v37, v235
	v_mov_b32_e32 v38, v35
	v_mov_b32_e32 v39, v36
	v_mov_b32_e32 v35, v37
	v_pk_add_f32 v[34:35], v[38:39], v[34:35]
	s_nop 0
	v_add_f32_e32 v34, v34, v35
	v_fmamk_f32 v34, v34, 0x3a800000, v184
	v_rsq_f32_e32 v34, v34
	s_nop 0
	v_pk_mul_f32 v[28:29], v[28:29], v[34:35] op_sel_hi:[1,0]
	s_nop 0
	v_mul_f32_e32 v35, 0xbfb8aa3b, v28
	v_exp_f32_e32 v35, v35
	s_nop 0
	v_add_f32_e32 v35, 1.0, v35
	v_rcp_f32_e32 v36, v35
	v_mul_f32_e32 v35, 0xbfb8aa3b, v29
	v_exp_f32_e32 v35, v35
	s_nop 0
	v_add_f32_e32 v35, 1.0, v35
	v_rcp_f32_e32 v37, v35
	v_pk_mul_f32 v[24:25], v[24:25], v[34:35] op_sel_hi:[1,0]
	v_pk_mul_f32 v[26:27], v[26:27], v[34:35] op_sel_hi:[1,0]
	v_pk_mul_f32 v[20:21], v[20:21], v[34:35] op_sel_hi:[1,0]
	v_pk_mul_f32 v[28:29], v[28:29], v[36:37]
	v_pk_mul_f32 v[16:17], v[16:17], v[34:35] op_sel_hi:[1,0]
	v_pk_mul_f32 v[24:25], v[24:25], v[28:29]
	v_pk_mul_f32 v[28:29], v[30:31], v[34:35] op_sel_hi:[1,0]
	v_cvt_pk_bf16_f32 v24, v24, v25
	v_mul_f32_e32 v30, 0xbfb8aa3b, v28
	v_mul_f32_e32 v31, 0xbfb8aa3b, v29
	v_exp_f32_e32 v30, v30
	v_exp_f32_e32 v31, v31
	v_pk_mul_f32 v[18:19], v[18:19], v[34:35] op_sel_hi:[1,0]
	v_add_f32_e32 v30, 1.0, v30
	v_add_f32_e32 v31, 1.0, v31
	v_rcp_f32_e32 v30, v30
	v_rcp_f32_e32 v31, v31
	s_nop 0
	v_pk_mul_f32 v[28:29], v[28:29], v[30:31]
	s_nop 0
	v_pk_mul_f32 v[26:27], v[26:27], v[28:29]
	s_nop 0
	v_cvt_pk_bf16_f32 v25, v26, v27
	v_lshl_add_u64 v[26:27], v[32:33], 0, v[120:121]
	global_store_dwordx2 v[26:27], v[24:25], off
	v_mul_f32_e32 v24, 0xbfb8aa3b, v20
	v_mul_f32_e32 v25, 0xbfb8aa3b, v21
	v_exp_f32_e32 v24, v24
	v_exp_f32_e32 v25, v25
	v_add_f32_e32 v24, 1.0, v24
	v_add_f32_e32 v25, 1.0, v25
	v_rcp_f32_e32 v24, v24
	v_rcp_f32_e32 v25, v25
	s_nop 0
	v_pk_mul_f32 v[20:21], v[20:21], v[24:25]
	s_nop 0
	v_pk_mul_f32 v[16:17], v[16:17], v[20:21]
	v_pk_mul_f32 v[20:21], v[22:23], v[34:35] op_sel_hi:[1,0]
	v_cvt_pk_bf16_f32 v16, v16, v17
	v_mul_f32_e32 v22, 0xbfb8aa3b, v20
	v_mul_f32_e32 v23, 0xbfb8aa3b, v21
	v_exp_f32_e32 v22, v22
	v_exp_f32_e32 v23, v23
	v_add_f32_e32 v22, 1.0, v22
	v_add_f32_e32 v23, 1.0, v23
	v_rcp_f32_e32 v22, v22
	v_rcp_f32_e32 v23, v23
	s_nop 0
	v_pk_mul_f32 v[20:21], v[20:21], v[22:23]
	s_nop 0
	v_pk_mul_f32 v[18:19], v[18:19], v[20:21]
	s_nop 0
	v_cvt_pk_bf16_f32 v17, v18, v19
	v_add_u32_e32 v18, 0xb0, v140
	v_ashrrev_i32_e32 v19, 31, v18
	global_store_dwordx2 v[26:27], v[16:17], off offset:128
	v_mad_i64_i32 v[16:17], s[2:3], v18, s78, v[138:139]
	v_mov_b32_e32 v18, v236
	v_mov_b32_e32 v19, v237
	v_mov_b32_e32 v20, v238
	v_mov_b32_e32 v21, v239
	s_mov_b64 s[2:3], -1
	v_mov_b32_e32 v22, v19
	v_mov_b32_e32 v23, v20
	v_mov_b32_e32 v19, v21
	v_pk_add_f32 v[18:19], v[22:23], v[18:19]
	s_nop 0
	v_add_f32_e32 v18, v18, v19
	v_fmamk_f32 v18, v18, 0x3a800000, v184
	v_rsq_f32_e32 v18, v18
	s_nop 0
	v_pk_mul_f32 v[12:13], v[12:13], v[18:19] op_sel_hi:[1,0]
	s_nop 0
	v_mul_f32_e32 v19, 0xbfb8aa3b, v12
	v_exp_f32_e32 v19, v19
	s_nop 0
	v_add_f32_e32 v19, 1.0, v19
	v_rcp_f32_e32 v20, v19
	v_mul_f32_e32 v19, 0xbfb8aa3b, v13
	v_exp_f32_e32 v19, v19
	s_nop 0
	v_add_f32_e32 v19, 1.0, v19
	v_rcp_f32_e32 v21, v19
	v_pk_mul_f32 v[8:9], v[8:9], v[18:19] op_sel_hi:[1,0]
	v_pk_mul_f32 v[10:11], v[10:11], v[18:19] op_sel_hi:[1,0]
	v_pk_mul_f32 v[4:5], v[4:5], v[18:19] op_sel_hi:[1,0]
	v_pk_mul_f32 v[12:13], v[12:13], v[20:21]
	v_pk_mul_f32 v[0:1], v[0:1], v[18:19] op_sel_hi:[1,0]
	v_pk_mul_f32 v[8:9], v[8:9], v[12:13]
	v_pk_mul_f32 v[12:13], v[14:15], v[18:19] op_sel_hi:[1,0]
	v_cvt_pk_bf16_f32 v8, v8, v9
	v_mul_f32_e32 v14, 0xbfb8aa3b, v12
	v_mul_f32_e32 v15, 0xbfb8aa3b, v13
	v_exp_f32_e32 v14, v14
	v_exp_f32_e32 v15, v15
	v_pk_mul_f32 v[2:3], v[2:3], v[18:19] op_sel_hi:[1,0]
	v_add_f32_e32 v14, 1.0, v14
	v_add_f32_e32 v15, 1.0, v15
	v_rcp_f32_e32 v14, v14
	v_rcp_f32_e32 v15, v15
	s_nop 0
	v_pk_mul_f32 v[12:13], v[12:13], v[14:15]
	s_nop 0
	v_pk_mul_f32 v[10:11], v[10:11], v[12:13]
	s_nop 0
	v_cvt_pk_bf16_f32 v9, v10, v11
	v_lshl_add_u64 v[10:11], v[16:17], 0, v[120:121]
	global_store_dwordx2 v[10:11], v[8:9], off
	v_mul_f32_e32 v8, 0xbfb8aa3b, v4
	v_mul_f32_e32 v9, 0xbfb8aa3b, v5
	v_exp_f32_e32 v8, v8
	v_exp_f32_e32 v9, v9
	v_add_f32_e32 v8, 1.0, v8
	v_add_f32_e32 v9, 1.0, v9
	v_rcp_f32_e32 v8, v8
	v_rcp_f32_e32 v9, v9
	s_nop 0
	v_pk_mul_f32 v[4:5], v[4:5], v[8:9]
	s_nop 0
	v_pk_mul_f32 v[0:1], v[0:1], v[4:5]
	v_pk_mul_f32 v[4:5], v[6:7], v[18:19] op_sel_hi:[1,0]
	v_cvt_pk_bf16_f32 v0, v0, v1
	v_mul_f32_e32 v6, 0xbfb8aa3b, v4
	v_mul_f32_e32 v7, 0xbfb8aa3b, v5
	v_exp_f32_e32 v6, v6
	v_exp_f32_e32 v7, v7
	v_add_f32_e32 v6, 1.0, v6
	v_add_f32_e32 v7, 1.0, v7
	v_rcp_f32_e32 v6, v6
	v_rcp_f32_e32 v7, v7
	s_nop 0
	v_pk_mul_f32 v[4:5], v[4:5], v[6:7]
	s_nop 0
	v_pk_mul_f32 v[2:3], v[2:3], v[4:5]
	s_nop 0
	v_cvt_pk_bf16_f32 v1, v2, v3
	global_store_dwordx2 v[10:11], v[0:1], off offset:128
	s_cbranch_vccnz .LBB0_1301
	s_andn2_b64 vcc, exec, s[40:41]
	s_cbranch_vccnz .LBB0_1300
	s_barrier
	s_branch .LBB0_1300
